# Q2 dec Fourier-mix (128-row) gated epilogue: the 8 serial gate loads issued together with counted waits; on top of v139
# baseline (speedup 1.0000x reference)
.LBB0_678:
	s_or_b64 exec, exec, s[4:5]
	s_lshl_b32 s2, s31, 10
	s_lshl_b32 s3, s56, 7
	s_or_b32 s2, s2, s3
	v_lshrrev_b32_e32 v66, 1, v106
	s_addk_i32 s2, 0x2000
	v_and_b32_e32 v72, 24, v66
	v_ashrrev_i32_e32 v66, 2, v106
	v_and_b32_e32 v0, 0xc0, v106
	v_and_b32_e32 v66, 0xffffffc0, v66
	v_and_or_b32 v67, v106, 15, s2
	v_lshl_or_b32 v0, s30, 8, v0
	v_add_u32_e32 v66, v67, v66
	v_mov_b64_e32 v[70:71], s[22:23]
	v_or_b32_e32 v74, v0, v72
	v_mad_i64_i32 v[68:69], s[2:3], v66, s72, v[70:71]
	s_mov_b64 s[4:5], 0x73400
	v_lshlrev_b32_e32 v72, 1, v72
	v_mov_b32_e32 v73, v1
	v_lshl_add_u64 v[68:69], v[68:69], 0, s[4:5]
	v_lshl_add_u64 v[138:139], s[14:15], 0, v[72:73]
	v_lshlrev_b32_e32 v72, 1, v74
	v_lshl_add_u64 v[76:77], v[68:69], 0, v[72:73]
	s_mov_b64 s[98:99], 0x28000
	v_mov_b32_e32 v246, v76
	v_mov_b32_e32 v247, v77
	v_mov_b32_e32 v248, v76
	v_mov_b32_e32 v249, v77
	global_load_dwordx4 v[84:87], v[246:247], off
	v_lshl_add_u64 v[246:247], v[246:247], 0, s[98:99]
	global_load_dwordx4 v[88:91], v[246:247], off
	v_lshl_add_u64 v[246:247], v[246:247], 0, s[98:99]
	global_load_dwordx4 v[92:95], v[246:247], off
	v_lshl_add_u64 v[246:247], v[246:247], 0, s[98:99]
	global_load_dwordx4 v[96:99], v[246:247], off
	global_load_dwordx4 v[100:103], v[248:249], off offset:64
	v_lshl_add_u64 v[248:249], v[248:249], 0, s[98:99]
	global_load_dwordx4 v[108:111], v[248:249], off offset:64
	v_lshl_add_u64 v[248:249], v[248:249], 0, s[98:99]
	global_load_dwordx4 v[238:241], v[248:249], off offset:64
	v_lshl_add_u64 v[248:249], v[248:249], 0, s[98:99]
	global_load_dwordx4 v[242:245], v[248:249], off offset:64
	v_ashrrev_i32_e32 v67, 31, v66
	v_lshlrev_b32_e32 v0, 9, v0
	s_waitcnt vmcnt(7)
	v_mov_b32_e32 v76, v84
	v_mov_b32_e32 v77, v85
	v_mov_b32_e32 v78, v86
	v_mov_b32_e32 v79, v87
	v_lshlrev_b32_e32 v80, 16, v76
	v_mul_f32_e32 v75, 0xbfb8aa3b, v80
	v_exp_f32_e32 v75, v75
	v_and_b32_e32 v81, 0xffff0000, v76
	v_lshlrev_b32_e32 v76, 16, v77
	v_and_b32_e32 v77, 0xffff0000, v77
	v_add_f32_e32 v75, 1.0, v75
	v_rcp_f32_e32 v82, v75
	v_mul_f32_e32 v75, 0xbfb8aa3b, v81
	v_exp_f32_e32 v75, v75
	s_nop 0
	v_add_f32_e32 v75, 1.0, v75
	v_rcp_f32_e32 v83, v75
	s_nop 0
	v_pk_mul_f32 v[80:81], v[82:83], v[80:81]
	s_nop 0
	v_pk_mul_f32 v[62:63], v[62:63], v[80:81]
	s_nop 0
	v_cvt_pk_bf16_f32 v62, v62, v63
	v_mul_f32_e32 v63, 0xbfb8aa3b, v76
	v_exp_f32_e32 v63, v63
	s_nop 0
	v_add_f32_e32 v63, 1.0, v63
	v_rcp_f32_e32 v80, v63
	v_mul_f32_e32 v63, 0xbfb8aa3b, v77
	v_exp_f32_e32 v63, v63
	s_nop 0
	v_add_f32_e32 v63, 1.0, v63
	v_rcp_f32_e32 v81, v63
	s_nop 0
	v_pk_mul_f32 v[76:77], v[80:81], v[76:77]
	s_nop 0
	v_pk_mul_f32 v[64:65], v[64:65], v[76:77]
	s_nop 0
	v_cvt_pk_bf16_f32 v63, v64, v65
	v_lshlrev_b32_e32 v64, 16, v78
	v_mul_f32_e32 v75, 0xbfb8aa3b, v64
	v_exp_f32_e32 v75, v75
	v_and_b32_e32 v65, 0xffff0000, v78
	v_add_f32_e32 v75, 1.0, v75
	v_rcp_f32_e32 v76, v75
	v_mul_f32_e32 v75, 0xbfb8aa3b, v65
	v_exp_f32_e32 v75, v75
	s_nop 0
	v_add_f32_e32 v75, 1.0, v75
	v_rcp_f32_e32 v77, v75
	s_nop 0
	v_pk_mul_f32 v[64:65], v[76:77], v[64:65]
	s_nop 0
	v_pk_mul_f32 v[58:59], v[58:59], v[64:65]
	s_nop 0
	v_cvt_pk_bf16_f32 v64, v58, v59
	v_lshlrev_b32_e32 v58, 16, v79
	v_mul_f32_e32 v65, 0xbfb8aa3b, v58
	v_exp_f32_e32 v65, v65
	v_and_b32_e32 v59, 0xffff0000, v79
	v_add_f32_e32 v65, 1.0, v65
	v_rcp_f32_e32 v76, v65
	v_mul_f32_e32 v65, 0xbfb8aa3b, v59
	v_exp_f32_e32 v65, v65
	s_nop 0
	v_add_f32_e32 v65, 1.0, v65
	v_rcp_f32_e32 v77, v65
	s_nop 0
	v_pk_mul_f32 v[58:59], v[76:77], v[58:59]
	s_nop 0
	v_pk_mul_f32 v[58:59], v[60:61], v[58:59]
	s_nop 0
	v_cvt_pk_bf16_f32 v65, v58, v59
	v_lshl_add_u64 v[58:59], v[66:67], 0, v[0:1]
	v_lshlrev_b64 v[58:59], 6, v[58:59]
	v_lshl_add_u64 v[58:59], v[138:139], 0, v[58:59]
	global_store_dwordx4 v[58:59], v[62:65], off
	v_or_b32_e32 v58, 16, v66
	v_mad_i64_i32 v[60:61], s[2:3], v58, s72, v[70:71]
	v_lshl_add_u64 v[60:61], v[60:61], 0, s[4:5]
	v_lshl_add_u64 v[62:63], v[60:61], 0, v[72:73]
	v_ashrrev_i32_e32 v59, 31, v58
	s_waitcnt vmcnt(7)
	v_mov_b32_e32 v62, v88
	v_mov_b32_e32 v63, v89
	v_mov_b32_e32 v64, v90
	v_mov_b32_e32 v65, v91
	v_lshlrev_b32_e32 v76, 16, v62
	v_and_b32_e32 v77, 0xffff0000, v62
	v_mul_f32_e32 v62, 0xbfb8aa3b, v76
	v_exp_f32_e32 v62, v62
	s_nop 0
	v_add_f32_e32 v62, 1.0, v62
	v_rcp_f32_e32 v78, v62
	v_mul_f32_e32 v62, 0xbfb8aa3b, v77
	v_exp_f32_e32 v62, v62
	s_nop 0
	v_add_f32_e32 v62, 1.0, v62
	v_rcp_f32_e32 v79, v62
	v_lshlrev_b32_e32 v62, 16, v63
	v_and_b32_e32 v63, 0xffff0000, v63
	v_pk_mul_f32 v[76:77], v[78:79], v[76:77]
	s_nop 0
	v_pk_mul_f32 v[54:55], v[54:55], v[76:77]
	s_nop 0
	v_cvt_pk_bf16_f32 v54, v54, v55
	v_mul_f32_e32 v55, 0xbfb8aa3b, v62
	v_exp_f32_e32 v55, v55
	s_nop 0
	v_add_f32_e32 v55, 1.0, v55
	v_rcp_f32_e32 v76, v55
	v_mul_f32_e32 v55, 0xbfb8aa3b, v63
	v_exp_f32_e32 v55, v55
	s_nop 0
	v_add_f32_e32 v55, 1.0, v55
	v_rcp_f32_e32 v77, v55
	s_nop 0
	v_pk_mul_f32 v[62:63], v[76:77], v[62:63]
	s_nop 0
	v_pk_mul_f32 v[56:57], v[56:57], v[62:63]
	s_nop 0
	v_cvt_pk_bf16_f32 v55, v56, v57
	v_lshlrev_b32_e32 v56, 16, v64
	v_and_b32_e32 v57, 0xffff0000, v64
	v_mul_f32_e32 v62, 0xbfb8aa3b, v56
	v_mul_f32_e32 v63, 0xbfb8aa3b, v57
	v_exp_f32_e32 v62, v62
	v_exp_f32_e32 v63, v63
	v_add_f32_e32 v62, 1.0, v62
	v_add_f32_e32 v63, 1.0, v63
	v_rcp_f32_e32 v62, v62
	v_rcp_f32_e32 v63, v63
	s_nop 0
	v_pk_mul_f32 v[56:57], v[62:63], v[56:57]
	s_nop 0
	v_pk_mul_f32 v[50:51], v[50:51], v[56:57]
	s_nop 0
	v_cvt_pk_bf16_f32 v56, v50, v51
	v_lshlrev_b32_e32 v50, 16, v65
	v_mul_f32_e32 v57, 0xbfb8aa3b, v50
	v_exp_f32_e32 v57, v57
	v_and_b32_e32 v51, 0xffff0000, v65
	v_add_f32_e32 v57, 1.0, v57
	v_rcp_f32_e32 v62, v57
	v_mul_f32_e32 v57, 0xbfb8aa3b, v51
	v_exp_f32_e32 v57, v57
	s_nop 0
	v_add_f32_e32 v57, 1.0, v57
	v_rcp_f32_e32 v63, v57
	s_nop 0
	v_pk_mul_f32 v[50:51], v[62:63], v[50:51]
	s_nop 0
	v_pk_mul_f32 v[50:51], v[52:53], v[50:51]
	s_nop 0
	v_cvt_pk_bf16_f32 v57, v50, v51
	v_lshl_add_u64 v[50:51], v[58:59], 0, v[0:1]
	v_lshlrev_b64 v[50:51], 6, v[50:51]
	v_lshl_add_u64 v[50:51], v[138:139], 0, v[50:51]
	global_store_dwordx4 v[50:51], v[54:57], off
	v_or_b32_e32 v50, 32, v66
	v_mad_i64_i32 v[52:53], s[2:3], v50, s72, v[70:71]
	v_lshl_add_u64 v[52:53], v[52:53], 0, s[4:5]
	v_lshl_add_u64 v[54:55], v[52:53], 0, v[72:73]
	v_ashrrev_i32_e32 v51, 31, v50
	s_waitcnt vmcnt(7)
	v_mov_b32_e32 v54, v92
	v_mov_b32_e32 v55, v93
	v_mov_b32_e32 v56, v94
	v_mov_b32_e32 v57, v95
	v_lshlrev_b32_e32 v62, 16, v54
	v_and_b32_e32 v63, 0xffff0000, v54
	v_mul_f32_e32 v54, 0xbfb8aa3b, v62
	v_exp_f32_e32 v54, v54
	s_nop 0
	v_add_f32_e32 v54, 1.0, v54
	v_rcp_f32_e32 v64, v54
	v_mul_f32_e32 v54, 0xbfb8aa3b, v63
	v_exp_f32_e32 v54, v54
	s_nop 0
	v_add_f32_e32 v54, 1.0, v54
	v_rcp_f32_e32 v65, v54
	v_lshlrev_b32_e32 v54, 16, v55
	v_and_b32_e32 v55, 0xffff0000, v55
	v_pk_mul_f32 v[62:63], v[64:65], v[62:63]
	s_nop 0
	v_pk_mul_f32 v[46:47], v[46:47], v[62:63]
	s_nop 0
	v_cvt_pk_bf16_f32 v46, v46, v47
	v_mul_f32_e32 v47, 0xbfb8aa3b, v54
	v_exp_f32_e32 v47, v47
	s_nop 0
	v_add_f32_e32 v47, 1.0, v47
	v_rcp_f32_e32 v62, v47
	v_mul_f32_e32 v47, 0xbfb8aa3b, v55
	v_exp_f32_e32 v47, v47
	s_nop 0
	v_add_f32_e32 v47, 1.0, v47
	v_rcp_f32_e32 v63, v47
	s_nop 0
	v_pk_mul_f32 v[54:55], v[62:63], v[54:55]
	s_nop 0
	v_pk_mul_f32 v[48:49], v[48:49], v[54:55]
	s_nop 0
	v_cvt_pk_bf16_f32 v47, v48, v49
	v_lshlrev_b32_e32 v48, 16, v56
	v_and_b32_e32 v49, 0xffff0000, v56
	v_mul_f32_e32 v54, 0xbfb8aa3b, v48
	v_mul_f32_e32 v55, 0xbfb8aa3b, v49
	v_exp_f32_e32 v54, v54
	v_exp_f32_e32 v55, v55
	v_add_f32_e32 v54, 1.0, v54
	v_add_f32_e32 v55, 1.0, v55
	v_rcp_f32_e32 v54, v54
	v_rcp_f32_e32 v55, v55
	s_nop 0
	v_pk_mul_f32 v[48:49], v[54:55], v[48:49]
	s_nop 0
	v_pk_mul_f32 v[42:43], v[42:43], v[48:49]
	s_nop 0
	v_cvt_pk_bf16_f32 v48, v42, v43
	v_lshlrev_b32_e32 v42, 16, v57
	v_mul_f32_e32 v49, 0xbfb8aa3b, v42
	v_exp_f32_e32 v49, v49
	v_and_b32_e32 v43, 0xffff0000, v57
	v_add_f32_e32 v49, 1.0, v49
	v_rcp_f32_e32 v54, v49
	v_mul_f32_e32 v49, 0xbfb8aa3b, v43
	v_exp_f32_e32 v49, v49
	s_nop 0
	v_add_f32_e32 v49, 1.0, v49
	v_rcp_f32_e32 v55, v49
	s_nop 0
	v_pk_mul_f32 v[42:43], v[54:55], v[42:43]
	s_nop 0
	v_pk_mul_f32 v[42:43], v[44:45], v[42:43]
	s_nop 0
	v_cvt_pk_bf16_f32 v49, v42, v43
	v_lshl_add_u64 v[42:43], v[50:51], 0, v[0:1]
	v_lshlrev_b64 v[42:43], 6, v[42:43]
	v_lshl_add_u64 v[42:43], v[138:139], 0, v[42:43]
	global_store_dwordx4 v[42:43], v[46:49], off
	v_or_b32_e32 v42, 48, v66
	v_mad_i64_i32 v[44:45], s[2:3], v42, s72, v[70:71]
	v_lshl_add_u64 v[44:45], v[44:45], 0, s[4:5]
	v_lshl_add_u64 v[46:47], v[44:45], 0, v[72:73]
	v_ashrrev_i32_e32 v43, 31, v42
	s_waitcnt vmcnt(7)
	v_mov_b32_e32 v46, v96
	v_mov_b32_e32 v47, v97
	v_mov_b32_e32 v48, v98
	v_mov_b32_e32 v49, v99
	v_lshlrev_b32_e32 v54, 16, v46
	v_and_b32_e32 v55, 0xffff0000, v46
	v_mul_f32_e32 v46, 0xbfb8aa3b, v54
	v_exp_f32_e32 v46, v46
	s_nop 0
	v_add_f32_e32 v46, 1.0, v46
	v_rcp_f32_e32 v56, v46
	v_mul_f32_e32 v46, 0xbfb8aa3b, v55
	v_exp_f32_e32 v46, v46
	s_nop 0
	v_add_f32_e32 v46, 1.0, v46
	v_rcp_f32_e32 v57, v46
	v_lshlrev_b32_e32 v46, 16, v47
	v_and_b32_e32 v47, 0xffff0000, v47
	v_pk_mul_f32 v[54:55], v[56:57], v[54:55]
	s_nop 0
	v_pk_mul_f32 v[38:39], v[38:39], v[54:55]
	s_nop 0
	v_cvt_pk_bf16_f32 v38, v38, v39
	v_mul_f32_e32 v39, 0xbfb8aa3b, v46
	v_exp_f32_e32 v39, v39
	s_nop 0
	v_add_f32_e32 v39, 1.0, v39
	v_rcp_f32_e32 v54, v39
	v_mul_f32_e32 v39, 0xbfb8aa3b, v47
	v_exp_f32_e32 v39, v39
	s_nop 0
	v_add_f32_e32 v39, 1.0, v39
	v_rcp_f32_e32 v55, v39
	s_nop 0
	v_pk_mul_f32 v[46:47], v[54:55], v[46:47]
	s_nop 0
	v_pk_mul_f32 v[40:41], v[40:41], v[46:47]
	s_nop 0
	v_cvt_pk_bf16_f32 v39, v40, v41
	v_lshlrev_b32_e32 v40, 16, v48
	v_and_b32_e32 v41, 0xffff0000, v48
	v_mul_f32_e32 v46, 0xbfb8aa3b, v40
	v_mul_f32_e32 v47, 0xbfb8aa3b, v41
	v_exp_f32_e32 v46, v46
	v_exp_f32_e32 v47, v47
	v_add_f32_e32 v46, 1.0, v46
	v_add_f32_e32 v47, 1.0, v47
	v_rcp_f32_e32 v46, v46
	v_rcp_f32_e32 v47, v47
	s_nop 0
	v_pk_mul_f32 v[40:41], v[46:47], v[40:41]
	s_nop 0
	v_pk_mul_f32 v[34:35], v[34:35], v[40:41]
	s_nop 0
	v_cvt_pk_bf16_f32 v40, v34, v35
	v_lshlrev_b32_e32 v34, 16, v49
	v_mul_f32_e32 v41, 0xbfb8aa3b, v34
	v_exp_f32_e32 v41, v41
	v_and_b32_e32 v35, 0xffff0000, v49
	v_add_f32_e32 v41, 1.0, v41
	v_rcp_f32_e32 v46, v41
	v_mul_f32_e32 v41, 0xbfb8aa3b, v35
	v_exp_f32_e32 v41, v41
	s_nop 0
	v_add_f32_e32 v41, 1.0, v41
	v_rcp_f32_e32 v47, v41
	s_nop 0
	v_pk_mul_f32 v[34:35], v[46:47], v[34:35]
	s_nop 0
	v_pk_mul_f32 v[34:35], v[36:37], v[34:35]
	s_nop 0
	v_cvt_pk_bf16_f32 v41, v34, v35
	v_lshl_add_u64 v[34:35], v[42:43], 0, v[0:1]
	v_lshlrev_b64 v[34:35], 6, v[34:35]
	v_lshl_add_u64 v[34:35], v[138:139], 0, v[34:35]
	global_store_dwordx4 v[34:35], v[38:41], off
	v_or_b32_e32 v34, 32, v74
	v_lshlrev_b32_e32 v0, 9, v34
	v_lshlrev_b32_e32 v34, 1, v34
	v_mov_b32_e32 v35, v1
	v_lshl_add_u64 v[36:37], v[68:69], 0, v[34:35]
	v_and_b32_e32 v0, 0x3c000, v0
	s_waitcnt vmcnt(7)
	v_mov_b32_e32 v36, v100
	v_mov_b32_e32 v37, v101
	v_mov_b32_e32 v38, v102
	v_mov_b32_e32 v39, v103
	v_lshlrev_b32_e32 v40, 16, v36
	v_and_b32_e32 v41, 0xffff0000, v36
	v_mul_f32_e32 v36, 0xbfb8aa3b, v40
	v_exp_f32_e32 v36, v36
	s_nop 0
	v_add_f32_e32 v36, 1.0, v36
	v_rcp_f32_e32 v46, v36
	v_mul_f32_e32 v36, 0xbfb8aa3b, v41
	v_exp_f32_e32 v36, v36
	s_nop 0
	v_add_f32_e32 v36, 1.0, v36
	v_rcp_f32_e32 v47, v36
	v_lshlrev_b32_e32 v36, 16, v37
	v_and_b32_e32 v37, 0xffff0000, v37
	v_pk_mul_f32 v[40:41], v[46:47], v[40:41]
	s_nop 0
	v_pk_mul_f32 v[30:31], v[30:31], v[40:41]
	s_nop 0
	v_cvt_pk_bf16_f32 v30, v30, v31
	v_mul_f32_e32 v31, 0xbfb8aa3b, v36
	v_exp_f32_e32 v31, v31
	s_nop 0
	v_add_f32_e32 v31, 1.0, v31
	v_rcp_f32_e32 v40, v31
	v_mul_f32_e32 v31, 0xbfb8aa3b, v37
	v_exp_f32_e32 v31, v31
	s_nop 0
	v_add_f32_e32 v31, 1.0, v31
	v_rcp_f32_e32 v41, v31
	s_nop 0
	v_pk_mul_f32 v[36:37], v[40:41], v[36:37]
	s_nop 0
	v_pk_mul_f32 v[32:33], v[32:33], v[36:37]
	s_nop 0
	v_cvt_pk_bf16_f32 v31, v32, v33
	v_lshlrev_b32_e32 v32, 16, v38
	v_and_b32_e32 v33, 0xffff0000, v38
	v_mul_f32_e32 v36, 0xbfb8aa3b, v32
	v_mul_f32_e32 v37, 0xbfb8aa3b, v33
	v_exp_f32_e32 v36, v36
	v_exp_f32_e32 v37, v37
	v_add_f32_e32 v36, 1.0, v36
	v_add_f32_e32 v37, 1.0, v37
	v_rcp_f32_e32 v36, v36
	v_rcp_f32_e32 v37, v37
	s_nop 0
	v_pk_mul_f32 v[32:33], v[36:37], v[32:33]
	s_nop 0
	v_pk_mul_f32 v[26:27], v[26:27], v[32:33]
	s_nop 0
	v_cvt_pk_bf16_f32 v32, v26, v27
	v_lshlrev_b32_e32 v26, 16, v39
	v_mul_f32_e32 v33, 0xbfb8aa3b, v26
	v_exp_f32_e32 v33, v33
	v_and_b32_e32 v27, 0xffff0000, v39
	v_add_f32_e32 v33, 1.0, v33
	v_rcp_f32_e32 v36, v33
	v_mul_f32_e32 v33, 0xbfb8aa3b, v27
	v_exp_f32_e32 v33, v33
	s_nop 0
	v_add_f32_e32 v33, 1.0, v33
	v_rcp_f32_e32 v37, v33
	s_nop 0
	v_pk_mul_f32 v[26:27], v[36:37], v[26:27]
	s_nop 0
	v_pk_mul_f32 v[26:27], v[28:29], v[26:27]
	s_nop 0
	v_cvt_pk_bf16_f32 v33, v26, v27
	v_lshl_add_u64 v[26:27], v[0:1], 0, v[66:67]
	v_lshlrev_b64 v[26:27], 6, v[26:27]
	v_lshl_add_u64 v[26:27], v[138:139], 0, v[26:27]
	global_store_dwordx4 v[26:27], v[30:33], off
	v_lshl_add_u64 v[26:27], v[60:61], 0, v[34:35]
	s_waitcnt vmcnt(7)
	v_mov_b32_e32 v26, v108
	v_mov_b32_e32 v27, v109
	v_mov_b32_e32 v28, v110
	v_mov_b32_e32 v29, v111
	v_lshlrev_b32_e32 v30, 16, v26
	v_and_b32_e32 v31, 0xffff0000, v26
	v_mul_f32_e32 v26, 0xbfb8aa3b, v30
	v_exp_f32_e32 v26, v26
	s_nop 0
	v_add_f32_e32 v26, 1.0, v26
	v_rcp_f32_e32 v32, v26
	v_mul_f32_e32 v26, 0xbfb8aa3b, v31
	v_exp_f32_e32 v26, v26
	s_nop 0
	v_add_f32_e32 v26, 1.0, v26
	v_rcp_f32_e32 v33, v26
	v_lshlrev_b32_e32 v26, 16, v27
	v_and_b32_e32 v27, 0xffff0000, v27
	v_pk_mul_f32 v[30:31], v[32:33], v[30:31]
	s_nop 0
	v_pk_mul_f32 v[22:23], v[22:23], v[30:31]
	s_nop 0
	v_cvt_pk_bf16_f32 v22, v22, v23
	v_mul_f32_e32 v23, 0xbfb8aa3b, v26
	v_exp_f32_e32 v23, v23
	s_nop 0
	v_add_f32_e32 v23, 1.0, v23
	v_rcp_f32_e32 v30, v23
	v_mul_f32_e32 v23, 0xbfb8aa3b, v27
	v_exp_f32_e32 v23, v23
	s_nop 0
	v_add_f32_e32 v23, 1.0, v23
	v_rcp_f32_e32 v31, v23
	s_nop 0
	v_pk_mul_f32 v[26:27], v[30:31], v[26:27]
	s_nop 0
	v_pk_mul_f32 v[24:25], v[24:25], v[26:27]
	s_nop 0
	v_cvt_pk_bf16_f32 v23, v24, v25
	v_lshlrev_b32_e32 v24, 16, v28
	v_and_b32_e32 v25, 0xffff0000, v28
	v_mul_f32_e32 v26, 0xbfb8aa3b, v24
	v_mul_f32_e32 v27, 0xbfb8aa3b, v25
	v_exp_f32_e32 v26, v26
	v_exp_f32_e32 v27, v27
	v_add_f32_e32 v26, 1.0, v26
	v_add_f32_e32 v27, 1.0, v27
	v_rcp_f32_e32 v26, v26
	v_rcp_f32_e32 v27, v27
	s_nop 0
	v_pk_mul_f32 v[24:25], v[26:27], v[24:25]
	s_nop 0
	v_pk_mul_f32 v[18:19], v[18:19], v[24:25]
	s_nop 0
	v_cvt_pk_bf16_f32 v24, v18, v19
	v_lshlrev_b32_e32 v18, 16, v29
	v_mul_f32_e32 v25, 0xbfb8aa3b, v18
	v_exp_f32_e32 v25, v25
	v_and_b32_e32 v19, 0xffff0000, v29
	v_add_f32_e32 v25, 1.0, v25
	v_rcp_f32_e32 v26, v25
	v_mul_f32_e32 v25, 0xbfb8aa3b, v19
	v_exp_f32_e32 v25, v25
	s_nop 0
	v_add_f32_e32 v25, 1.0, v25
	v_rcp_f32_e32 v27, v25
	s_nop 0
	v_pk_mul_f32 v[18:19], v[26:27], v[18:19]
	s_nop 0
	v_pk_mul_f32 v[18:19], v[20:21], v[18:19]
	s_nop 0
	v_cvt_pk_bf16_f32 v25, v18, v19
	v_lshl_add_u64 v[18:19], v[0:1], 0, v[58:59]
	v_lshlrev_b64 v[18:19], 6, v[18:19]
	v_lshl_add_u64 v[18:19], v[138:139], 0, v[18:19]
	global_store_dwordx4 v[18:19], v[22:25], off
	v_lshl_add_u64 v[18:19], v[52:53], 0, v[34:35]
	s_waitcnt vmcnt(7)
	v_mov_b32_e32 v18, v238
	v_mov_b32_e32 v19, v239
	v_mov_b32_e32 v20, v240
	v_mov_b32_e32 v21, v241
	v_lshlrev_b32_e32 v22, 16, v18
	v_and_b32_e32 v23, 0xffff0000, v18
	v_mul_f32_e32 v18, 0xbfb8aa3b, v22
	v_exp_f32_e32 v18, v18
	s_nop 0
	v_add_f32_e32 v18, 1.0, v18
	v_rcp_f32_e32 v24, v18
	v_mul_f32_e32 v18, 0xbfb8aa3b, v23
	v_exp_f32_e32 v18, v18
	s_nop 0
	v_add_f32_e32 v18, 1.0, v18
	v_rcp_f32_e32 v25, v18
	v_lshlrev_b32_e32 v18, 16, v19
	v_and_b32_e32 v19, 0xffff0000, v19
	v_pk_mul_f32 v[22:23], v[24:25], v[22:23]
	s_nop 0
	v_pk_mul_f32 v[14:15], v[14:15], v[22:23]
	s_nop 0
	v_cvt_pk_bf16_f32 v14, v14, v15
	v_mul_f32_e32 v15, 0xbfb8aa3b, v18
	v_exp_f32_e32 v15, v15
	s_nop 0
	v_add_f32_e32 v15, 1.0, v15
	v_rcp_f32_e32 v22, v15
	v_mul_f32_e32 v15, 0xbfb8aa3b, v19
	v_exp_f32_e32 v15, v15
	s_nop 0
	v_add_f32_e32 v15, 1.0, v15
	v_rcp_f32_e32 v23, v15
	s_nop 0
	v_pk_mul_f32 v[18:19], v[22:23], v[18:19]
	s_nop 0
	v_pk_mul_f32 v[16:17], v[16:17], v[18:19]
	s_nop 0
	v_cvt_pk_bf16_f32 v15, v16, v17
	v_lshlrev_b32_e32 v16, 16, v20
	v_and_b32_e32 v17, 0xffff0000, v20
	v_mul_f32_e32 v18, 0xbfb8aa3b, v16
	v_mul_f32_e32 v19, 0xbfb8aa3b, v17
	v_exp_f32_e32 v18, v18
	v_exp_f32_e32 v19, v19
	v_add_f32_e32 v18, 1.0, v18
	v_add_f32_e32 v19, 1.0, v19
	v_rcp_f32_e32 v18, v18
	v_rcp_f32_e32 v19, v19
	s_nop 0
	v_pk_mul_f32 v[16:17], v[18:19], v[16:17]
	s_nop 0
	v_pk_mul_f32 v[10:11], v[10:11], v[16:17]
	s_nop 0
	v_cvt_pk_bf16_f32 v16, v10, v11
	v_lshlrev_b32_e32 v10, 16, v21
	v_mul_f32_e32 v17, 0xbfb8aa3b, v10
	v_exp_f32_e32 v17, v17
	v_and_b32_e32 v11, 0xffff0000, v21
	v_add_f32_e32 v17, 1.0, v17
	v_rcp_f32_e32 v18, v17
	v_mul_f32_e32 v17, 0xbfb8aa3b, v11
	v_exp_f32_e32 v17, v17
	s_nop 0
	v_add_f32_e32 v17, 1.0, v17
	v_rcp_f32_e32 v19, v17
	s_nop 0
	v_pk_mul_f32 v[10:11], v[18:19], v[10:11]
	s_nop 0
	v_pk_mul_f32 v[10:11], v[12:13], v[10:11]
	s_nop 0
	v_cvt_pk_bf16_f32 v17, v10, v11
	v_lshl_add_u64 v[10:11], v[0:1], 0, v[50:51]
	v_lshlrev_b64 v[10:11], 6, v[10:11]
	v_lshl_add_u64 v[10:11], v[138:139], 0, v[10:11]
	global_store_dwordx4 v[10:11], v[14:17], off
	v_lshl_add_u64 v[10:11], v[44:45], 0, v[34:35]
	s_waitcnt vmcnt(7)
	v_mov_b32_e32 v10, v242
	v_mov_b32_e32 v11, v243
	v_mov_b32_e32 v12, v244
	v_mov_b32_e32 v13, v245
	v_lshlrev_b32_e32 v14, 16, v10
	v_and_b32_e32 v15, 0xffff0000, v10
	v_mul_f32_e32 v10, 0xbfb8aa3b, v14
	v_exp_f32_e32 v10, v10
	s_nop 0
	v_add_f32_e32 v10, 1.0, v10
	v_rcp_f32_e32 v16, v10
	v_mul_f32_e32 v10, 0xbfb8aa3b, v15
	v_exp_f32_e32 v10, v10
	s_nop 0
	v_add_f32_e32 v10, 1.0, v10
	v_rcp_f32_e32 v17, v10
	v_lshlrev_b32_e32 v10, 16, v11
	v_and_b32_e32 v11, 0xffff0000, v11
	v_pk_mul_f32 v[14:15], v[16:17], v[14:15]
	s_nop 0
	v_pk_mul_f32 v[6:7], v[6:7], v[14:15]
	s_nop 0
	v_cvt_pk_bf16_f32 v6, v6, v7
	v_mul_f32_e32 v7, 0xbfb8aa3b, v10
	v_exp_f32_e32 v7, v7
	s_nop 0
	v_add_f32_e32 v7, 1.0, v7
	v_rcp_f32_e32 v14, v7
	v_mul_f32_e32 v7, 0xbfb8aa3b, v11
	v_exp_f32_e32 v7, v7
	s_nop 0
	v_add_f32_e32 v7, 1.0, v7
	v_rcp_f32_e32 v15, v7
	s_nop 0
	v_pk_mul_f32 v[10:11], v[14:15], v[10:11]
	s_nop 0
	v_pk_mul_f32 v[8:9], v[8:9], v[10:11]
	s_nop 0
	v_cvt_pk_bf16_f32 v7, v8, v9
	v_lshlrev_b32_e32 v8, 16, v12
	v_and_b32_e32 v9, 0xffff0000, v12
	v_mul_f32_e32 v10, 0xbfb8aa3b, v8
	v_mul_f32_e32 v11, 0xbfb8aa3b, v9
	v_exp_f32_e32 v10, v10
	v_exp_f32_e32 v11, v11
	v_add_f32_e32 v10, 1.0, v10
	v_add_f32_e32 v11, 1.0, v11
	v_rcp_f32_e32 v10, v10
	v_rcp_f32_e32 v11, v11
	s_nop 0
	v_pk_mul_f32 v[8:9], v[10:11], v[8:9]
	s_nop 0
	v_pk_mul_f32 v[2:3], v[2:3], v[8:9]
	s_nop 0
	v_cvt_pk_bf16_f32 v8, v2, v3
	v_lshlrev_b32_e32 v2, 16, v13
	v_mul_f32_e32 v9, 0xbfb8aa3b, v2
	v_exp_f32_e32 v9, v9
	v_and_b32_e32 v3, 0xffff0000, v13
	v_add_f32_e32 v9, 1.0, v9
	v_rcp_f32_e32 v10, v9
	v_mul_f32_e32 v9, 0xbfb8aa3b, v3
	v_exp_f32_e32 v9, v9
	s_nop 0
	v_add_f32_e32 v9, 1.0, v9
	v_rcp_f32_e32 v11, v9
	s_nop 0
	v_pk_mul_f32 v[2:3], v[10:11], v[2:3]
	s_nop 0
	v_pk_mul_f32 v[2:3], v[4:5], v[2:3]
	s_nop 0
	v_cvt_pk_bf16_f32 v9, v2, v3
	v_lshl_add_u64 v[2:3], v[0:1], 0, v[42:43]
